# first K-iteration peeled (C=0 MFMAs, no accumulator zeroing movs) in the QKV, W_o and both down-projection loops too
# speedup vs baseline: 1.0080x; 1.0060x over previous
.LBB0_211:
	s_ashr_i32 s17, s16, 31
	s_lshl_b64 s[18:19], s[16:17], 19
	s_add_u32 s18, s68, s18
	s_addc_u32 s19, s69, s19
	s_and_b64 s[20:21], s[0:1], exec
	s_cselect_b32 s17, s19, s25
	s_cselect_b32 s44, s18, s24
	s_ashr_i32 s15, s14, 31
	s_lshl_b64 s[20:21], s[14:15], 19
	s_add_u32 s20, s3, s20
	s_addc_u32 s21, s6, s21
	s_and_b64 s[28:29], s[0:1], exec
	s_cselect_b32 s15, s21, s27
	s_cselect_b32 s45, s20, s26
	s_add_u32 s24, s24, 0x40080
	s_addc_u32 s25, s25, 0
	s_add_u32 s46, s26, 0x100
	s_addc_u32 s47, s27, 0
	s_mov_b32 s70, -2
	ds_read_b128 v[146:149], v153
	ds_read_b128 v[156:159], v153 offset:1024
	ds_read_b128 v[160:163], v153 offset:2048
	ds_read_b128 v[164:167], v153 offset:3072
	ds_read_b128 v[174:177], v154
	ds_read_b128 v[178:181], v154 offset:1024
	ds_read_b128 v[182:185], v154 offset:2048
	ds_read_b128 v[186:189], v154 offset:3072
	s_add_u32 s26, s24, 0xfffc0080
	s_addc_u32 s27, s25, -1
	s_cmp_eq_u32 s70, 12
	s_cselect_b32 s29, s17, s27
	s_cselect_b32 s28, s44, s26
	s_cselect_b32 s27, s15, s47
	s_cselect_b32 s26, s45, s46
	s_add_i32 m0, s23, 0xc000
	ds_read_b128 v[190:193], v155
	ds_read_b128 v[194:197], v155 offset:1024
	ds_read_b128 v[198:201], v155 offset:2048
	ds_read_b128 v[202:205], v155 offset:3072
	ds_read_b128 v[206:209], v155 offset:4096
	ds_read_b128 v[210:213], v155 offset:5120
	ds_read_b128 v[214:217], v155 offset:6144
	ds_read_b128 v[218:221], v155 offset:7168
	global_load_lds_dwordx4 v138, s[24:25]
	s_add_i32 m0, s23, 0xe000
	s_nop 0
	global_load_lds_dwordx4 v140, s[24:25]
	s_waitcnt vmcnt(8)
	s_waitcnt lgkmcnt(0)
	s_barrier
	s_setprio 1
	v_mfma_f32_16x16x32_bf16 v[126:129], v[146:149], v[190:193], 0
	v_mfma_f32_16x16x32_bf16 v[122:125], v[160:163], v[190:193], 0
	v_mfma_f32_16x16x32_bf16 v[118:121], v[146:149], v[198:201], 0
	v_mfma_f32_16x16x32_bf16 v[110:113], v[160:163], v[198:201], 0
	v_mfma_f32_16x16x32_bf16 v[102:105], v[146:149], v[206:209], 0
	v_mfma_f32_16x16x32_bf16 v[94:97], v[160:163], v[206:209], 0
	v_mfma_f32_16x16x32_bf16 v[86:89], v[146:149], v[214:217], 0
	v_mfma_f32_16x16x32_bf16 v[78:81], v[160:163], v[214:217], 0
	v_mfma_f32_16x16x32_bf16 v[126:129], v[156:159], v[194:197], v[126:129]
	v_mfma_f32_16x16x32_bf16 v[122:125], v[164:167], v[194:197], v[122:125]
	v_mfma_f32_16x16x32_bf16 v[118:121], v[156:159], v[202:205], v[118:121]
	v_mfma_f32_16x16x32_bf16 v[110:113], v[164:167], v[202:205], v[110:113]
	v_mfma_f32_16x16x32_bf16 v[102:105], v[156:159], v[210:213], v[102:105]
	v_mfma_f32_16x16x32_bf16 v[94:97], v[164:167], v[210:213], v[94:97]
	v_mfma_f32_16x16x32_bf16 v[86:89], v[156:159], v[218:221], v[86:89]
	v_mfma_f32_16x16x32_bf16 v[78:81], v[164:167], v[218:221], v[78:81]
	v_mfma_f32_16x16x32_bf16 v[114:117], v[174:177], v[190:193], 0
	v_mfma_f32_16x16x32_bf16 v[106:109], v[182:185], v[190:193], 0
	v_mfma_f32_16x16x32_bf16 v[98:101], v[174:177], v[198:201], 0
	v_mfma_f32_16x16x32_bf16 v[90:93], v[182:185], v[198:201], 0
	v_mfma_f32_16x16x32_bf16 v[82:85], v[174:177], v[206:209], 0
	v_mfma_f32_16x16x32_bf16 v[74:77], v[182:185], v[206:209], 0
	v_mfma_f32_16x16x32_bf16 v[70:73], v[174:177], v[214:217], 0
	v_mfma_f32_16x16x32_bf16 v[66:69], v[182:185], v[214:217], 0
	v_mfma_f32_16x16x32_bf16 v[114:117], v[178:181], v[194:197], v[114:117]
	v_mfma_f32_16x16x32_bf16 v[106:109], v[186:189], v[194:197], v[106:109]
	v_mfma_f32_16x16x32_bf16 v[98:101], v[178:181], v[202:205], v[98:101]
	v_mfma_f32_16x16x32_bf16 v[90:93], v[186:189], v[202:205], v[90:93]
	v_mfma_f32_16x16x32_bf16 v[82:85], v[178:181], v[210:213], v[82:85]
	v_mfma_f32_16x16x32_bf16 v[74:77], v[186:189], v[210:213], v[74:77]
	v_mfma_f32_16x16x32_bf16 v[70:73], v[178:181], v[218:221], v[70:73]
	v_mfma_f32_16x16x32_bf16 v[66:69], v[186:189], v[218:221], v[66:69]
	s_setprio 0
	s_barrier
	s_add_u32 s98, s26, 0x80
	s_addc_u32 s99, s27, 0
	s_add_u32 s100, s28, 0x80
	s_addc_u32 s101, s29, 0
	s_add_i32 s71, s40, s7
	s_mov_b32 m0, s71
	ds_read_b128 v[190:193], v155 offset:16384
	ds_read_b128 v[194:197], v155 offset:17408
	ds_read_b128 v[198:201], v155 offset:18432
	ds_read_b128 v[202:205], v155 offset:19456
	ds_read_b128 v[206:209], v155 offset:20480
	ds_read_b128 v[210:213], v155 offset:21504
	ds_read_b128 v[214:217], v155 offset:22528
	ds_read_b128 v[218:221], v155 offset:23552
	global_load_lds_dwordx4 v134, s[26:27]
	s_add_i32 m0, s71, 0x2000
	s_add_u32 s74, s26, 0x40000
	s_addc_u32 s75, s27, 0
	s_add_i32 s71, s41, s7
	global_load_lds_dwordx4 v130, s[26:27]
	s_mov_b32 m0, s71
	s_nop 0
	global_load_lds_dwordx4 v134, s[74:75]
	s_add_i32 m0, s71, 0x2000
	s_nop 0
	global_load_lds_dwordx4 v130, s[74:75]
	s_mov_b32 m0, s23
	s_nop 0
	global_load_lds_dwordx4 v136, s[28:29]
	s_mov_b32 m0, s31
	s_nop 0
	global_load_lds_dwordx4 v132, s[28:29]
	s_waitcnt vmcnt(8)
	s_waitcnt lgkmcnt(0)
	s_barrier
	s_setprio 1
	v_mfma_f32_16x16x32_bf16 v[62:65], v[146:149], v[190:193], 0
	v_mfma_f32_16x16x32_bf16 v[58:61], v[160:163], v[190:193], 0
	v_mfma_f32_16x16x32_bf16 v[54:57], v[146:149], v[198:201], 0
	v_mfma_f32_16x16x32_bf16 v[46:49], v[160:163], v[198:201], 0
	v_mfma_f32_16x16x32_bf16 v[38:41], v[146:149], v[206:209], 0
	v_mfma_f32_16x16x32_bf16 v[30:33], v[160:163], v[206:209], 0
	v_mfma_f32_16x16x32_bf16 v[22:25], v[146:149], v[214:217], 0
	v_mfma_f32_16x16x32_bf16 v[14:17], v[160:163], v[214:217], 0
	v_mfma_f32_16x16x32_bf16 v[62:65], v[156:159], v[194:197], v[62:65]
	v_mfma_f32_16x16x32_bf16 v[58:61], v[164:167], v[194:197], v[58:61]
	v_mfma_f32_16x16x32_bf16 v[54:57], v[156:159], v[202:205], v[54:57]
	v_mfma_f32_16x16x32_bf16 v[46:49], v[164:167], v[202:205], v[46:49]
	v_mfma_f32_16x16x32_bf16 v[38:41], v[156:159], v[210:213], v[38:41]
	v_mfma_f32_16x16x32_bf16 v[30:33], v[164:167], v[210:213], v[30:33]
	v_mfma_f32_16x16x32_bf16 v[22:25], v[156:159], v[218:221], v[22:25]
	v_mfma_f32_16x16x32_bf16 v[14:17], v[164:167], v[218:221], v[14:17]
	v_mfma_f32_16x16x32_bf16 v[50:53], v[174:177], v[190:193], 0
	v_mfma_f32_16x16x32_bf16 v[42:45], v[182:185], v[190:193], 0
	v_mfma_f32_16x16x32_bf16 v[34:37], v[174:177], v[198:201], 0
	v_mfma_f32_16x16x32_bf16 v[26:29], v[182:185], v[198:201], 0
	v_mfma_f32_16x16x32_bf16 v[18:21], v[174:177], v[206:209], 0
	v_mfma_f32_16x16x32_bf16 v[10:13], v[182:185], v[206:209], 0
	v_mfma_f32_16x16x32_bf16 v[6:9], v[174:177], v[214:217], 0
	v_mfma_f32_16x16x32_bf16 v[2:5], v[182:185], v[214:217], 0
	v_mfma_f32_16x16x32_bf16 v[50:53], v[178:181], v[194:197], v[50:53]
	v_mfma_f32_16x16x32_bf16 v[42:45], v[186:189], v[194:197], v[42:45]
	v_mfma_f32_16x16x32_bf16 v[34:37], v[178:181], v[202:205], v[34:37]
	v_mfma_f32_16x16x32_bf16 v[26:29], v[186:189], v[202:205], v[26:29]
	v_mfma_f32_16x16x32_bf16 v[18:21], v[178:181], v[210:213], v[18:21]
	v_mfma_f32_16x16x32_bf16 v[10:13], v[186:189], v[210:213], v[10:13]
	v_mfma_f32_16x16x32_bf16 v[6:9], v[178:181], v[218:221], v[6:9]
	v_mfma_f32_16x16x32_bf16 v[2:5], v[186:189], v[218:221], v[2:5]
	s_setprio 0
	s_barrier
	s_add_i32 s71, 0, 0x18000
	v_add_u32_e32 v1, s71, v151
	s_add_i32 s74, 0, 0x1c000
	ds_read_b128 v[146:149], v1
	ds_read_b128 v[156:159], v1 offset:1024
	ds_read_b128 v[160:163], v1 offset:2048
	ds_read_b128 v[164:167], v1 offset:3072
	v_add_u32_e32 v1, s74, v151
	ds_read_b128 v[174:177], v1
	ds_read_b128 v[178:181], v1 offset:1024
	ds_read_b128 v[182:185], v1 offset:2048
	ds_read_b128 v[186:189], v1 offset:3072
	s_add_u32 s28, s28, 0x40000
	s_addc_u32 s29, s29, 0
	s_mov_b32 m0, s34
	ds_read_b128 v[190:193], v155 offset:32768
	ds_read_b128 v[194:197], v155 offset:33792
	ds_read_b128 v[198:201], v155 offset:34816
	ds_read_b128 v[202:205], v155 offset:35840
	ds_read_b128 v[206:209], v155 offset:36864
	ds_read_b128 v[210:213], v155 offset:37888
	ds_read_b128 v[214:217], v155 offset:38912
	ds_read_b128 v[218:221], v155 offset:39936
	global_load_lds_dwordx4 v136, s[28:29]
	s_mov_b32 m0, s35
	s_nop 0
	global_load_lds_dwordx4 v132, s[28:29]
	s_waitcnt vmcnt(8)
	s_waitcnt lgkmcnt(0)
	s_barrier
	s_setprio 1
	v_mfma_f32_16x16x32_bf16 v[126:129], v[146:149], v[190:193], v[126:129]
	v_mfma_f32_16x16x32_bf16 v[122:125], v[160:163], v[190:193], v[122:125]
	v_mfma_f32_16x16x32_bf16 v[118:121], v[146:149], v[198:201], v[118:121]
	v_mfma_f32_16x16x32_bf16 v[110:113], v[160:163], v[198:201], v[110:113]
	v_mfma_f32_16x16x32_bf16 v[102:105], v[146:149], v[206:209], v[102:105]
	v_mfma_f32_16x16x32_bf16 v[94:97], v[160:163], v[206:209], v[94:97]
	v_mfma_f32_16x16x32_bf16 v[86:89], v[146:149], v[214:217], v[86:89]
	v_mfma_f32_16x16x32_bf16 v[78:81], v[160:163], v[214:217], v[78:81]
	v_mfma_f32_16x16x32_bf16 v[126:129], v[156:159], v[194:197], v[126:129]
	v_mfma_f32_16x16x32_bf16 v[122:125], v[164:167], v[194:197], v[122:125]
	v_mfma_f32_16x16x32_bf16 v[118:121], v[156:159], v[202:205], v[118:121]
	v_mfma_f32_16x16x32_bf16 v[110:113], v[164:167], v[202:205], v[110:113]
	v_mfma_f32_16x16x32_bf16 v[102:105], v[156:159], v[210:213], v[102:105]
	v_mfma_f32_16x16x32_bf16 v[94:97], v[164:167], v[210:213], v[94:97]
	v_mfma_f32_16x16x32_bf16 v[86:89], v[156:159], v[218:221], v[86:89]
	v_mfma_f32_16x16x32_bf16 v[78:81], v[164:167], v[218:221], v[78:81]
	v_mfma_f32_16x16x32_bf16 v[114:117], v[174:177], v[190:193], v[114:117]
	v_mfma_f32_16x16x32_bf16 v[106:109], v[182:185], v[190:193], v[106:109]
	v_mfma_f32_16x16x32_bf16 v[98:101], v[174:177], v[198:201], v[98:101]
	v_mfma_f32_16x16x32_bf16 v[90:93], v[182:185], v[198:201], v[90:93]
	v_mfma_f32_16x16x32_bf16 v[82:85], v[174:177], v[206:209], v[82:85]
	v_mfma_f32_16x16x32_bf16 v[74:77], v[182:185], v[206:209], v[74:77]
	v_mfma_f32_16x16x32_bf16 v[70:73], v[174:177], v[214:217], v[70:73]
	v_mfma_f32_16x16x32_bf16 v[66:69], v[182:185], v[214:217], v[66:69]
	v_mfma_f32_16x16x32_bf16 v[114:117], v[178:181], v[194:197], v[114:117]
	v_mfma_f32_16x16x32_bf16 v[106:109], v[186:189], v[194:197], v[106:109]
	v_mfma_f32_16x16x32_bf16 v[98:101], v[178:181], v[202:205], v[98:101]
	v_mfma_f32_16x16x32_bf16 v[90:93], v[186:189], v[202:205], v[90:93]
	v_mfma_f32_16x16x32_bf16 v[82:85], v[178:181], v[210:213], v[82:85]
	v_mfma_f32_16x16x32_bf16 v[74:77], v[186:189], v[210:213], v[74:77]
	v_mfma_f32_16x16x32_bf16 v[70:73], v[178:181], v[218:221], v[70:73]
	v_mfma_f32_16x16x32_bf16 v[66:69], v[186:189], v[218:221], v[66:69]
	s_setprio 0
	s_barrier
	s_add_i32 s28, s71, s7
	s_mov_b32 m0, s28
	ds_read_b128 v[190:193], v155 offset:49152
	ds_read_b128 v[194:197], v155 offset:50176
	ds_read_b128 v[198:201], v155 offset:51200
	ds_read_b128 v[202:205], v155 offset:52224
	ds_read_b128 v[206:209], v155 offset:53248
	ds_read_b128 v[210:213], v155 offset:54272
	ds_read_b128 v[214:217], v155 offset:55296
	ds_read_b128 v[218:221], v155 offset:56320
	global_load_lds_dwordx4 v134, s[98:99]
	s_add_i32 m0, s28, 0x2000
	s_add_u32 s26, s26, 0x40080
	s_addc_u32 s27, s27, 0
	s_add_i32 s28, s74, s7
	global_load_lds_dwordx4 v130, s[98:99]
	s_mov_b32 m0, s28
	s_nop 0
	global_load_lds_dwordx4 v134, s[26:27]
	s_add_i32 m0, s28, 0x2000
	s_nop 0
	global_load_lds_dwordx4 v130, s[26:27]
	s_mov_b32 m0, s37
	s_nop 0
	global_load_lds_dwordx4 v136, s[100:101]
	s_mov_b32 m0, s38
	s_nop 0
	global_load_lds_dwordx4 v132, s[100:101]
	s_waitcnt vmcnt(8)
	s_waitcnt lgkmcnt(0)
	s_barrier
	s_setprio 1
	v_mfma_f32_16x16x32_bf16 v[62:65], v[146:149], v[190:193], v[62:65]
	v_mfma_f32_16x16x32_bf16 v[58:61], v[160:163], v[190:193], v[58:61]
	v_mfma_f32_16x16x32_bf16 v[54:57], v[146:149], v[198:201], v[54:57]
	v_mfma_f32_16x16x32_bf16 v[46:49], v[160:163], v[198:201], v[46:49]
	v_mfma_f32_16x16x32_bf16 v[38:41], v[146:149], v[206:209], v[38:41]
	v_mfma_f32_16x16x32_bf16 v[30:33], v[160:163], v[206:209], v[30:33]
	v_mfma_f32_16x16x32_bf16 v[22:25], v[146:149], v[214:217], v[22:25]
	v_mfma_f32_16x16x32_bf16 v[14:17], v[160:163], v[214:217], v[14:17]
	v_mfma_f32_16x16x32_bf16 v[62:65], v[156:159], v[194:197], v[62:65]
	v_mfma_f32_16x16x32_bf16 v[58:61], v[164:167], v[194:197], v[58:61]
	v_mfma_f32_16x16x32_bf16 v[54:57], v[156:159], v[202:205], v[54:57]
	v_mfma_f32_16x16x32_bf16 v[46:49], v[164:167], v[202:205], v[46:49]
	v_mfma_f32_16x16x32_bf16 v[38:41], v[156:159], v[210:213], v[38:41]
	v_mfma_f32_16x16x32_bf16 v[30:33], v[164:167], v[210:213], v[30:33]
	v_mfma_f32_16x16x32_bf16 v[22:25], v[156:159], v[218:221], v[22:25]
	v_mfma_f32_16x16x32_bf16 v[14:17], v[164:167], v[218:221], v[14:17]
	v_mfma_f32_16x16x32_bf16 v[50:53], v[174:177], v[190:193], v[50:53]
	v_mfma_f32_16x16x32_bf16 v[42:45], v[182:185], v[190:193], v[42:45]
	v_mfma_f32_16x16x32_bf16 v[34:37], v[174:177], v[198:201], v[34:37]
	v_mfma_f32_16x16x32_bf16 v[26:29], v[182:185], v[198:201], v[26:29]
	v_mfma_f32_16x16x32_bf16 v[18:21], v[174:177], v[206:209], v[18:21]
	v_mfma_f32_16x16x32_bf16 v[10:13], v[182:185], v[206:209], v[10:13]
	v_mfma_f32_16x16x32_bf16 v[6:9], v[174:177], v[214:217], v[6:9]
	v_mfma_f32_16x16x32_bf16 v[2:5], v[182:185], v[214:217], v[2:5]
	v_mfma_f32_16x16x32_bf16 v[50:53], v[178:181], v[194:197], v[50:53]
	v_mfma_f32_16x16x32_bf16 v[42:45], v[186:189], v[194:197], v[42:45]
	v_mfma_f32_16x16x32_bf16 v[34:37], v[178:181], v[202:205], v[34:37]
	v_mfma_f32_16x16x32_bf16 v[26:29], v[186:189], v[202:205], v[26:29]
	v_mfma_f32_16x16x32_bf16 v[18:21], v[178:181], v[210:213], v[18:21]
	v_mfma_f32_16x16x32_bf16 v[10:13], v[186:189], v[210:213], v[10:13]
	v_mfma_f32_16x16x32_bf16 v[6:9], v[178:181], v[218:221], v[6:9]
	v_mfma_f32_16x16x32_bf16 v[2:5], v[186:189], v[218:221], v[2:5]
	s_setprio 0
	s_barrier
	s_add_i32 s70, s70, 2
	s_add_u32 s24, s24, 0x100
	s_addc_u32 s25, s25, 0
	s_add_u32 s46, s46, 0x100
	s_addc_u32 s47, s47, 0
	s_cmp_gt_u32 s70, 13

.LBB0_449:
	s_ashr_i32 s21, s20, 31
	s_lshl_b64 s[22:23], s[20:21], 19
	s_add_u32 s22, s52, s22
	s_addc_u32 s23, s53, s23
	s_and_b64 s[24:25], s[4:5], exec
	s_cselect_b32 s21, s23, s31
	s_cselect_b32 s27, s22, s30
	s_ashr_i32 s19, s18, 31
	s_lshl_b64 s[24:25], s[18:19], 19
	s_add_u32 s24, s3, s24
	s_addc_u32 s25, s6, s25
	s_and_b64 s[36:37], s[4:5], exec
	s_cselect_b32 s19, s25, s35
	s_cselect_b32 s29, s24, s34
	s_add_u32 s30, s30, 0x40080
	s_addc_u32 s31, s31, 0
	s_add_u32 s55, s34, 0x100
	s_addc_u32 s70, s35, 0
	s_mov_b32 s71, -2
	s_waitcnt lgkmcnt(0)
	ds_read_b128 v[98:101], v213
	ds_read_b128 v[102:105], v213 offset:1024
	ds_read_b128 v[106:109], v213 offset:2048
	ds_read_b128 v[110:113], v213 offset:3072
	ds_read_b128 v[146:149], v214
	ds_read_b128 v[150:153], v214 offset:1024
	ds_read_b128 v[154:157], v214 offset:2048
	ds_read_b128 v[158:161], v214 offset:3072
	s_add_u32 s34, s30, 0xfffc0080
	s_addc_u32 s35, s31, -1
	s_cmp_eq_u32 s71, 12
	s_cselect_b32 s37, s21, s35
	s_cselect_b32 s36, s27, s34
	s_cselect_b32 s35, s19, s70
	s_cselect_b32 s34, s29, s55
	s_add_i32 m0, s38, 0xc000
	ds_read_b128 v[182:185], v215
	ds_read_b128 v[186:189], v215 offset:1024
	ds_read_b128 v[190:193], v215 offset:2048
	ds_read_b128 v[194:197], v215 offset:3072
	ds_read_b128 v[198:201], v215 offset:4096
	ds_read_b128 v[202:205], v215 offset:5120
	ds_read_b128 v[206:209], v215 offset:6144
	ds_read_b128 v[218:221], v215 offset:7168
	global_load_lds_dwordx4 v174, s[30:31]
	s_add_i32 m0, s38, 0xe000
	s_nop 0
	global_load_lds_dwordx4 v176, s[30:31]
	s_waitcnt vmcnt(8)
	s_waitcnt lgkmcnt(0)
	s_barrier
	s_setprio 1
	v_mfma_f32_16x16x32_bf16 v[142:145], v[98:101], v[182:185], 0
	v_mfma_f32_16x16x32_bf16 v[138:141], v[106:109], v[182:185], 0
	v_mfma_f32_16x16x32_bf16 v[126:129], v[98:101], v[190:193], 0
	v_mfma_f32_16x16x32_bf16 v[122:125], v[106:109], v[190:193], 0
	v_mfma_f32_16x16x32_bf16 v[94:97], v[98:101], v[198:201], 0
	v_mfma_f32_16x16x32_bf16 v[90:93], v[106:109], v[198:201], 0
	v_mfma_f32_16x16x32_bf16 v[78:81], v[98:101], v[206:209], 0
	v_mfma_f32_16x16x32_bf16 v[74:77], v[106:109], v[206:209], 0
	v_mfma_f32_16x16x32_bf16 v[142:145], v[102:105], v[186:189], v[142:145]
	v_mfma_f32_16x16x32_bf16 v[138:141], v[110:113], v[186:189], v[138:141]
	v_mfma_f32_16x16x32_bf16 v[126:129], v[102:105], v[194:197], v[126:129]
	v_mfma_f32_16x16x32_bf16 v[122:125], v[110:113], v[194:197], v[122:125]
	v_mfma_f32_16x16x32_bf16 v[94:97], v[102:105], v[202:205], v[94:97]
	v_mfma_f32_16x16x32_bf16 v[90:93], v[110:113], v[202:205], v[90:93]
	v_mfma_f32_16x16x32_bf16 v[78:81], v[102:105], v[218:221], v[78:81]
	v_mfma_f32_16x16x32_bf16 v[74:77], v[110:113], v[218:221], v[74:77]
	v_mfma_f32_16x16x32_bf16 v[134:137], v[146:149], v[182:185], 0
	v_mfma_f32_16x16x32_bf16 v[130:133], v[154:157], v[182:185], 0
	v_mfma_f32_16x16x32_bf16 v[118:121], v[146:149], v[190:193], 0
	v_mfma_f32_16x16x32_bf16 v[114:117], v[154:157], v[190:193], 0
	v_mfma_f32_16x16x32_bf16 v[86:89], v[146:149], v[198:201], 0
	v_mfma_f32_16x16x32_bf16 v[82:85], v[154:157], v[198:201], 0
	v_mfma_f32_16x16x32_bf16 v[70:73], v[146:149], v[206:209], 0
	v_mfma_f32_16x16x32_bf16 v[66:69], v[154:157], v[206:209], 0
	v_mfma_f32_16x16x32_bf16 v[134:137], v[150:153], v[186:189], v[134:137]
	v_mfma_f32_16x16x32_bf16 v[130:133], v[158:161], v[186:189], v[130:133]
	v_mfma_f32_16x16x32_bf16 v[118:121], v[150:153], v[194:197], v[118:121]
	v_mfma_f32_16x16x32_bf16 v[114:117], v[158:161], v[194:197], v[114:117]
	v_mfma_f32_16x16x32_bf16 v[86:89], v[150:153], v[202:205], v[86:89]
	v_mfma_f32_16x16x32_bf16 v[82:85], v[158:161], v[202:205], v[82:85]
	v_mfma_f32_16x16x32_bf16 v[70:73], v[150:153], v[218:221], v[70:73]
	v_mfma_f32_16x16x32_bf16 v[66:69], v[158:161], v[218:221], v[66:69]
	s_setprio 0
	s_barrier
	s_add_u32 s98, s34, 0x80
	s_addc_u32 s99, s35, 0
	s_add_u32 s100, s36, 0x80
	s_addc_u32 s101, s37, 0
	s_add_i32 s74, s51, s7
	s_mov_b32 m0, s74
	ds_read_b128 v[182:185], v215 offset:16384
	ds_read_b128 v[186:189], v215 offset:17408
	ds_read_b128 v[190:193], v215 offset:18432
	ds_read_b128 v[194:197], v215 offset:19456
	ds_read_b128 v[198:201], v215 offset:20480
	ds_read_b128 v[202:205], v215 offset:21504
	ds_read_b128 v[206:209], v215 offset:22528
	ds_read_b128 v[218:221], v215 offset:23552
	s_cmp_eq_u32 s71, 12
	s_cselect_b64 exec, 0, -1
	s_cmp_lg_u32 s33, 0x100
	s_cselect_b64 exec, -1, exec
	global_load_lds_dwordx4 v164, s[34:35]
	s_add_i32 m0, s74, 0x2000
	s_add_u32 s74, s34, 0x40000
	s_addc_u32 s75, s35, 0
	s_add_i32 s76, s54, s7
	global_load_lds_dwordx4 v168, s[34:35]
	s_mov_b32 m0, s76
	s_nop 0
	global_load_lds_dwordx4 v164, s[74:75]
	s_add_i32 m0, s76, 0x2000
	s_nop 0
	global_load_lds_dwordx4 v168, s[74:75]
	s_mov_b32 m0, s38
	s_nop 0
	global_load_lds_dwordx4 v162, s[36:37]
	s_mov_b32 m0, s39
	s_nop 0
	global_load_lds_dwordx4 v166, s[36:37]
	s_mov_b64 exec, -1
	s_waitcnt vmcnt(8)
	s_waitcnt lgkmcnt(0)
	s_barrier
	s_setprio 1
	v_mfma_f32_16x16x32_bf16 v[62:65], v[98:101], v[182:185], 0
	v_mfma_f32_16x16x32_bf16 v[58:61], v[106:109], v[182:185], 0
	v_mfma_f32_16x16x32_bf16 v[46:49], v[98:101], v[190:193], 0
	v_mfma_f32_16x16x32_bf16 v[42:45], v[106:109], v[190:193], 0
	v_mfma_f32_16x16x32_bf16 v[30:33], v[98:101], v[198:201], 0
	v_mfma_f32_16x16x32_bf16 v[26:29], v[106:109], v[198:201], 0
	v_mfma_f32_16x16x32_bf16 v[14:17], v[98:101], v[206:209], 0
	v_mfma_f32_16x16x32_bf16 v[10:13], v[106:109], v[206:209], 0
	v_mfma_f32_16x16x32_bf16 v[62:65], v[102:105], v[186:189], v[62:65]
	v_mfma_f32_16x16x32_bf16 v[58:61], v[110:113], v[186:189], v[58:61]
	v_mfma_f32_16x16x32_bf16 v[46:49], v[102:105], v[194:197], v[46:49]
	v_mfma_f32_16x16x32_bf16 v[42:45], v[110:113], v[194:197], v[42:45]
	v_mfma_f32_16x16x32_bf16 v[30:33], v[102:105], v[202:205], v[30:33]
	v_mfma_f32_16x16x32_bf16 v[26:29], v[110:113], v[202:205], v[26:29]
	v_mfma_f32_16x16x32_bf16 v[14:17], v[102:105], v[218:221], v[14:17]
	v_mfma_f32_16x16x32_bf16 v[10:13], v[110:113], v[218:221], v[10:13]
	v_mfma_f32_16x16x32_bf16 v[54:57], v[146:149], v[182:185], 0
	v_mfma_f32_16x16x32_bf16 v[50:53], v[154:157], v[182:185], 0
	v_mfma_f32_16x16x32_bf16 v[38:41], v[146:149], v[190:193], 0
	v_mfma_f32_16x16x32_bf16 v[34:37], v[154:157], v[190:193], 0
	v_mfma_f32_16x16x32_bf16 v[22:25], v[146:149], v[198:201], 0
	v_mfma_f32_16x16x32_bf16 v[18:21], v[154:157], v[198:201], 0
	v_mfma_f32_16x16x32_bf16 v[6:9], v[146:149], v[206:209], 0
	v_mfma_f32_16x16x32_bf16 v[2:5], v[154:157], v[206:209], 0
	v_mfma_f32_16x16x32_bf16 v[54:57], v[150:153], v[186:189], v[54:57]
	v_mfma_f32_16x16x32_bf16 v[50:53], v[158:161], v[186:189], v[50:53]
	v_mfma_f32_16x16x32_bf16 v[38:41], v[150:153], v[194:197], v[38:41]
	v_mfma_f32_16x16x32_bf16 v[34:37], v[158:161], v[194:197], v[34:37]
	v_mfma_f32_16x16x32_bf16 v[22:25], v[150:153], v[202:205], v[22:25]
	v_mfma_f32_16x16x32_bf16 v[18:21], v[158:161], v[202:205], v[18:21]
	v_mfma_f32_16x16x32_bf16 v[6:9], v[150:153], v[218:221], v[6:9]
	v_mfma_f32_16x16x32_bf16 v[2:5], v[158:161], v[218:221], v[2:5]
	s_setprio 0
	s_barrier
	s_add_i32 s74, 0, 0x18000
	v_add_u32_e32 v1, s74, v173
	s_add_i32 s75, 0, 0x1c000
	ds_read_b128 v[98:101], v1
	ds_read_b128 v[102:105], v1 offset:1024
	ds_read_b128 v[106:109], v1 offset:2048
	ds_read_b128 v[110:113], v1 offset:3072
	v_add_u32_e32 v1, s75, v173
	ds_read_b128 v[146:149], v1
	ds_read_b128 v[150:153], v1 offset:1024
	ds_read_b128 v[154:157], v1 offset:2048
	ds_read_b128 v[158:161], v1 offset:3072
	s_add_u32 s36, s36, 0x40000
	s_addc_u32 s37, s37, 0
	s_mov_b32 m0, s40
	ds_read_b128 v[182:185], v215 offset:32768
	ds_read_b128 v[186:189], v215 offset:33792
	ds_read_b128 v[190:193], v215 offset:34816
	ds_read_b128 v[194:197], v215 offset:35840
	ds_read_b128 v[198:201], v215 offset:36864
	ds_read_b128 v[202:205], v215 offset:37888
	ds_read_b128 v[206:209], v215 offset:38912
	ds_read_b128 v[218:221], v215 offset:39936
	s_cmp_eq_u32 s71, 12
	s_cselect_b64 exec, 0, -1
	s_cmp_lg_u32 s33, 0x100
	s_cselect_b64 exec, -1, exec
	global_load_lds_dwordx4 v162, s[36:37]
	s_mov_b32 m0, s41
	s_nop 0
	global_load_lds_dwordx4 v166, s[36:37]
	s_mov_b64 exec, -1
	s_waitcnt vmcnt(8)
	s_waitcnt lgkmcnt(0)
	s_barrier
	s_setprio 1
	v_mfma_f32_16x16x32_bf16 v[142:145], v[98:101], v[182:185], v[142:145]
	v_mfma_f32_16x16x32_bf16 v[138:141], v[106:109], v[182:185], v[138:141]
	v_mfma_f32_16x16x32_bf16 v[126:129], v[98:101], v[190:193], v[126:129]
	v_mfma_f32_16x16x32_bf16 v[122:125], v[106:109], v[190:193], v[122:125]
	v_mfma_f32_16x16x32_bf16 v[94:97], v[98:101], v[198:201], v[94:97]
	v_mfma_f32_16x16x32_bf16 v[90:93], v[106:109], v[198:201], v[90:93]
	v_mfma_f32_16x16x32_bf16 v[78:81], v[98:101], v[206:209], v[78:81]
	v_mfma_f32_16x16x32_bf16 v[74:77], v[106:109], v[206:209], v[74:77]
	v_mfma_f32_16x16x32_bf16 v[142:145], v[102:105], v[186:189], v[142:145]
	v_mfma_f32_16x16x32_bf16 v[138:141], v[110:113], v[186:189], v[138:141]
	v_mfma_f32_16x16x32_bf16 v[126:129], v[102:105], v[194:197], v[126:129]
	v_mfma_f32_16x16x32_bf16 v[122:125], v[110:113], v[194:197], v[122:125]
	v_mfma_f32_16x16x32_bf16 v[94:97], v[102:105], v[202:205], v[94:97]
	v_mfma_f32_16x16x32_bf16 v[90:93], v[110:113], v[202:205], v[90:93]
	v_mfma_f32_16x16x32_bf16 v[78:81], v[102:105], v[218:221], v[78:81]
	v_mfma_f32_16x16x32_bf16 v[74:77], v[110:113], v[218:221], v[74:77]
	v_mfma_f32_16x16x32_bf16 v[134:137], v[146:149], v[182:185], v[134:137]
	v_mfma_f32_16x16x32_bf16 v[130:133], v[154:157], v[182:185], v[130:133]
	v_mfma_f32_16x16x32_bf16 v[118:121], v[146:149], v[190:193], v[118:121]
	v_mfma_f32_16x16x32_bf16 v[114:117], v[154:157], v[190:193], v[114:117]
	v_mfma_f32_16x16x32_bf16 v[86:89], v[146:149], v[198:201], v[86:89]
	v_mfma_f32_16x16x32_bf16 v[82:85], v[154:157], v[198:201], v[82:85]
	v_mfma_f32_16x16x32_bf16 v[70:73], v[146:149], v[206:209], v[70:73]
	v_mfma_f32_16x16x32_bf16 v[66:69], v[154:157], v[206:209], v[66:69]
	v_mfma_f32_16x16x32_bf16 v[134:137], v[150:153], v[186:189], v[134:137]
	v_mfma_f32_16x16x32_bf16 v[130:133], v[158:161], v[186:189], v[130:133]
	v_mfma_f32_16x16x32_bf16 v[118:121], v[150:153], v[194:197], v[118:121]
	v_mfma_f32_16x16x32_bf16 v[114:117], v[158:161], v[194:197], v[114:117]
	v_mfma_f32_16x16x32_bf16 v[86:89], v[150:153], v[202:205], v[86:89]
	v_mfma_f32_16x16x32_bf16 v[82:85], v[158:161], v[202:205], v[82:85]
	v_mfma_f32_16x16x32_bf16 v[70:73], v[150:153], v[218:221], v[70:73]
	v_mfma_f32_16x16x32_bf16 v[66:69], v[158:161], v[218:221], v[66:69]
	s_setprio 0
	s_barrier
	s_add_i32 s36, s74, s7
	s_mov_b32 m0, s36
	ds_read_b128 v[182:185], v215 offset:49152
	ds_read_b128 v[186:189], v215 offset:50176
	ds_read_b128 v[190:193], v215 offset:51200
	ds_read_b128 v[194:197], v215 offset:52224
	ds_read_b128 v[198:201], v215 offset:53248
	ds_read_b128 v[202:205], v215 offset:54272
	ds_read_b128 v[206:209], v215 offset:55296
	ds_read_b128 v[218:221], v215 offset:56320
	s_cmp_eq_u32 s71, 12
	s_cselect_b64 exec, 0, -1
	s_cmp_lg_u32 s33, 0x100
	s_cselect_b64 exec, -1, exec
	global_load_lds_dwordx4 v164, s[98:99]
	s_add_i32 m0, s36, 0x2000
	s_add_u32 s34, s34, 0x40080
	s_addc_u32 s35, s35, 0
	s_add_i32 s36, s75, s7
	global_load_lds_dwordx4 v168, s[98:99]
	s_mov_b32 m0, s36
	s_nop 0
	global_load_lds_dwordx4 v164, s[34:35]
	s_add_i32 m0, s36, 0x2000
	s_nop 0
	global_load_lds_dwordx4 v168, s[34:35]
	s_mov_b32 m0, s47
	s_nop 0
	global_load_lds_dwordx4 v162, s[100:101]
	s_mov_b32 m0, s48
	s_nop 0
	global_load_lds_dwordx4 v166, s[100:101]
	s_mov_b64 exec, -1
	s_waitcnt vmcnt(8)
	s_waitcnt lgkmcnt(0)
	s_barrier
	s_setprio 1
	v_mfma_f32_16x16x32_bf16 v[62:65], v[98:101], v[182:185], v[62:65]
	v_mfma_f32_16x16x32_bf16 v[58:61], v[106:109], v[182:185], v[58:61]
	v_mfma_f32_16x16x32_bf16 v[46:49], v[98:101], v[190:193], v[46:49]
	v_mfma_f32_16x16x32_bf16 v[42:45], v[106:109], v[190:193], v[42:45]
	v_mfma_f32_16x16x32_bf16 v[30:33], v[98:101], v[198:201], v[30:33]
	v_mfma_f32_16x16x32_bf16 v[26:29], v[106:109], v[198:201], v[26:29]
	v_mfma_f32_16x16x32_bf16 v[14:17], v[98:101], v[206:209], v[14:17]
	v_mfma_f32_16x16x32_bf16 v[10:13], v[106:109], v[206:209], v[10:13]
	v_mfma_f32_16x16x32_bf16 v[62:65], v[102:105], v[186:189], v[62:65]
	v_mfma_f32_16x16x32_bf16 v[58:61], v[110:113], v[186:189], v[58:61]
	v_mfma_f32_16x16x32_bf16 v[46:49], v[102:105], v[194:197], v[46:49]
	v_mfma_f32_16x16x32_bf16 v[42:45], v[110:113], v[194:197], v[42:45]
	v_mfma_f32_16x16x32_bf16 v[30:33], v[102:105], v[202:205], v[30:33]
	v_mfma_f32_16x16x32_bf16 v[26:29], v[110:113], v[202:205], v[26:29]
	v_mfma_f32_16x16x32_bf16 v[14:17], v[102:105], v[218:221], v[14:17]
	v_mfma_f32_16x16x32_bf16 v[10:13], v[110:113], v[218:221], v[10:13]
	v_mfma_f32_16x16x32_bf16 v[54:57], v[146:149], v[182:185], v[54:57]
	v_mfma_f32_16x16x32_bf16 v[50:53], v[154:157], v[182:185], v[50:53]
	v_mfma_f32_16x16x32_bf16 v[38:41], v[146:149], v[190:193], v[38:41]
	v_mfma_f32_16x16x32_bf16 v[34:37], v[154:157], v[190:193], v[34:37]
	v_mfma_f32_16x16x32_bf16 v[22:25], v[146:149], v[198:201], v[22:25]
	v_mfma_f32_16x16x32_bf16 v[18:21], v[154:157], v[198:201], v[18:21]
	v_mfma_f32_16x16x32_bf16 v[6:9], v[146:149], v[206:209], v[6:9]
	v_mfma_f32_16x16x32_bf16 v[2:5], v[154:157], v[206:209], v[2:5]
	v_mfma_f32_16x16x32_bf16 v[54:57], v[150:153], v[186:189], v[54:57]
	v_mfma_f32_16x16x32_bf16 v[50:53], v[158:161], v[186:189], v[50:53]
	v_mfma_f32_16x16x32_bf16 v[38:41], v[150:153], v[194:197], v[38:41]
	v_mfma_f32_16x16x32_bf16 v[34:37], v[158:161], v[194:197], v[34:37]
	v_mfma_f32_16x16x32_bf16 v[22:25], v[150:153], v[202:205], v[22:25]
	v_mfma_f32_16x16x32_bf16 v[18:21], v[158:161], v[202:205], v[18:21]
	v_mfma_f32_16x16x32_bf16 v[6:9], v[150:153], v[218:221], v[6:9]
	v_mfma_f32_16x16x32_bf16 v[2:5], v[158:161], v[218:221], v[2:5]
	s_setprio 0
	s_barrier
	s_add_i32 s71, s71, 2
	s_add_u32 s30, s30, 0x100
	s_addc_u32 s31, s31, 0
	s_add_u32 s55, s55, 0x100
	s_addc_u32 s70, s70, 0
	s_cmp_gt_u32 s71, 13

.LBB0_732:
	s_add_u32 s24, s24, 0xb0080
	s_addc_u32 s25, s25, 0
	s_add_u32 s49, s26, 0x100
	s_addc_u32 s50, s27, 0
	s_mov_b32 s51, -2
	s_waitcnt lgkmcnt(0)
	ds_read_b128 v[78:81], v184
	ds_read_b128 v[86:89], v184 offset:1024
	ds_read_b128 v[90:93], v184 offset:2048
	ds_read_b128 v[94:97], v184 offset:3072
	ds_read_b128 v[146:149], v185
	ds_read_b128 v[150:153], v185 offset:1024
	ds_read_b128 v[176:179], v185 offset:2048
	ds_read_b128 v[180:183], v185 offset:3072
	s_add_u32 s26, s24, 0xfff50080
	s_addc_u32 s27, s25, -1
	s_cmp_eq_u32 s51, 40
	s_cselect_b32 s29, s9, s27
	s_cselect_b32 s28, s8, s26
	s_cselect_b32 s27, s23, s50
	s_cselect_b32 s26, s22, s49
	s_add_i32 m0, s34, 0xc000
	ds_read_b128 v[188:191], v186
	ds_read_b128 v[192:195], v186 offset:1024
	ds_read_b128 v[196:199], v186 offset:2048
	ds_read_b128 v[200:203], v186 offset:3072
	ds_read_b128 v[204:207], v186 offset:4096
	ds_read_b128 v[208:211], v186 offset:5120
	ds_read_b128 v[212:215], v186 offset:6144
	ds_read_b128 v[216:219], v186 offset:7168
	global_load_lds_dwordx4 v162, s[24:25]
	s_add_i32 m0, s34, 0xe000
	s_nop 0
	global_load_lds_dwordx4 v164, s[24:25]
	s_waitcnt vmcnt(8)
	s_waitcnt lgkmcnt(0)
	s_barrier
	s_setprio 1
	v_mfma_f32_16x16x32_bf16 v[142:145], v[78:81], v[188:191], 0
	v_mfma_f32_16x16x32_bf16 v[138:141], v[90:93], v[188:191], 0
	v_mfma_f32_16x16x32_bf16 v[126:129], v[78:81], v[196:199], 0
	v_mfma_f32_16x16x32_bf16 v[122:125], v[90:93], v[196:199], 0
	v_mfma_f32_16x16x32_bf16 v[110:113], v[78:81], v[204:207], 0
	v_mfma_f32_16x16x32_bf16 v[106:109], v[90:93], v[204:207], 0
	v_mfma_f32_16x16x32_bf16 v[82:85], v[78:81], v[212:215], 0
	v_mfma_f32_16x16x32_bf16 v[74:77], v[90:93], v[212:215], 0
	v_mfma_f32_16x16x32_bf16 v[142:145], v[86:89], v[192:195], v[142:145]
	v_mfma_f32_16x16x32_bf16 v[138:141], v[94:97], v[192:195], v[138:141]
	v_mfma_f32_16x16x32_bf16 v[126:129], v[86:89], v[200:203], v[126:129]
	v_mfma_f32_16x16x32_bf16 v[122:125], v[94:97], v[200:203], v[122:125]
	v_mfma_f32_16x16x32_bf16 v[110:113], v[86:89], v[208:211], v[110:113]
	v_mfma_f32_16x16x32_bf16 v[106:109], v[94:97], v[208:211], v[106:109]
	v_mfma_f32_16x16x32_bf16 v[82:85], v[86:89], v[216:219], v[82:85]
	v_mfma_f32_16x16x32_bf16 v[74:77], v[94:97], v[216:219], v[74:77]
	v_mfma_f32_16x16x32_bf16 v[134:137], v[146:149], v[188:191], 0
	v_mfma_f32_16x16x32_bf16 v[130:133], v[176:179], v[188:191], 0
	v_mfma_f32_16x16x32_bf16 v[118:121], v[146:149], v[196:199], 0
	v_mfma_f32_16x16x32_bf16 v[114:117], v[176:179], v[196:199], 0
	v_mfma_f32_16x16x32_bf16 v[102:105], v[146:149], v[204:207], 0
	v_mfma_f32_16x16x32_bf16 v[98:101], v[176:179], v[204:207], 0
	v_mfma_f32_16x16x32_bf16 v[70:73], v[146:149], v[212:215], 0
	v_mfma_f32_16x16x32_bf16 v[66:69], v[176:179], v[212:215], 0
	v_mfma_f32_16x16x32_bf16 v[134:137], v[150:153], v[192:195], v[134:137]
	v_mfma_f32_16x16x32_bf16 v[130:133], v[180:183], v[192:195], v[130:133]
	v_mfma_f32_16x16x32_bf16 v[118:121], v[150:153], v[200:203], v[118:121]
	v_mfma_f32_16x16x32_bf16 v[114:117], v[180:183], v[200:203], v[114:117]
	v_mfma_f32_16x16x32_bf16 v[102:105], v[150:153], v[208:211], v[102:105]
	v_mfma_f32_16x16x32_bf16 v[98:101], v[180:183], v[208:211], v[98:101]
	v_mfma_f32_16x16x32_bf16 v[70:73], v[150:153], v[216:219], v[70:73]
	v_mfma_f32_16x16x32_bf16 v[66:69], v[180:183], v[216:219], v[66:69]
	s_setprio 0
	s_barrier
	s_add_u32 s98, s26, 0x80
	s_addc_u32 s99, s27, 0
	s_add_u32 s100, s28, 0x80
	s_addc_u32 s101, s29, 0
	s_add_i32 s54, s43, s31
	s_mov_b32 m0, s54
	ds_read_b128 v[188:191], v186 offset:16384
	ds_read_b128 v[192:195], v186 offset:17408
	ds_read_b128 v[196:199], v186 offset:18432
	ds_read_b128 v[200:203], v186 offset:19456
	ds_read_b128 v[204:207], v186 offset:20480
	ds_read_b128 v[208:211], v186 offset:21504
	ds_read_b128 v[212:215], v186 offset:22528
	ds_read_b128 v[216:219], v186 offset:23552
	s_cmp_eq_u32 s51, 40
	s_cselect_b64 exec, 0, -1
	s_cmp_lg_u32 s33, 0x100
	s_cselect_b64 exec, -1, exec
	global_load_lds_dwordx4 v156, s[26:27]
	s_add_i32 m0, s54, 0x2000
	s_add_u32 s54, s26, 0xb0000
	s_addc_u32 s55, s27, 0
	s_add_i32 s58, s44, s31
	global_load_lds_dwordx4 v160, s[26:27]
	s_mov_b32 m0, s58
	s_nop 0
	global_load_lds_dwordx4 v156, s[54:55]
	s_add_i32 m0, s58, 0x2000
	s_nop 0
	global_load_lds_dwordx4 v160, s[54:55]
	s_mov_b32 m0, s34
	s_nop 0
	global_load_lds_dwordx4 v154, s[28:29]
	s_mov_b32 m0, s35
	s_nop 0
	global_load_lds_dwordx4 v158, s[28:29]
	s_mov_b64 exec, -1
	s_waitcnt vmcnt(8)
	s_waitcnt lgkmcnt(0)
	s_barrier
	s_setprio 1
	v_mfma_f32_16x16x32_bf16 v[62:65], v[78:81], v[188:191], 0
	v_mfma_f32_16x16x32_bf16 v[58:61], v[90:93], v[188:191], 0
	v_mfma_f32_16x16x32_bf16 v[46:49], v[78:81], v[196:199], 0
	v_mfma_f32_16x16x32_bf16 v[42:45], v[90:93], v[196:199], 0
	v_mfma_f32_16x16x32_bf16 v[30:33], v[78:81], v[204:207], 0
	v_mfma_f32_16x16x32_bf16 v[26:29], v[90:93], v[204:207], 0
	v_mfma_f32_16x16x32_bf16 v[14:17], v[78:81], v[212:215], 0
	v_mfma_f32_16x16x32_bf16 v[10:13], v[90:93], v[212:215], 0
	v_mfma_f32_16x16x32_bf16 v[62:65], v[86:89], v[192:195], v[62:65]
	v_mfma_f32_16x16x32_bf16 v[58:61], v[94:97], v[192:195], v[58:61]
	v_mfma_f32_16x16x32_bf16 v[46:49], v[86:89], v[200:203], v[46:49]
	v_mfma_f32_16x16x32_bf16 v[42:45], v[94:97], v[200:203], v[42:45]
	v_mfma_f32_16x16x32_bf16 v[30:33], v[86:89], v[208:211], v[30:33]
	v_mfma_f32_16x16x32_bf16 v[26:29], v[94:97], v[208:211], v[26:29]
	v_mfma_f32_16x16x32_bf16 v[14:17], v[86:89], v[216:219], v[14:17]
	v_mfma_f32_16x16x32_bf16 v[10:13], v[94:97], v[216:219], v[10:13]
	v_mfma_f32_16x16x32_bf16 v[54:57], v[146:149], v[188:191], 0
	v_mfma_f32_16x16x32_bf16 v[50:53], v[176:179], v[188:191], 0
	v_mfma_f32_16x16x32_bf16 v[38:41], v[146:149], v[196:199], 0
	v_mfma_f32_16x16x32_bf16 v[34:37], v[176:179], v[196:199], 0
	v_mfma_f32_16x16x32_bf16 v[22:25], v[146:149], v[204:207], 0
	v_mfma_f32_16x16x32_bf16 v[18:21], v[176:179], v[204:207], 0
	v_mfma_f32_16x16x32_bf16 v[6:9], v[146:149], v[212:215], 0
	v_mfma_f32_16x16x32_bf16 v[2:5], v[176:179], v[212:215], 0
	v_mfma_f32_16x16x32_bf16 v[54:57], v[150:153], v[192:195], v[54:57]
	v_mfma_f32_16x16x32_bf16 v[50:53], v[180:183], v[192:195], v[50:53]
	v_mfma_f32_16x16x32_bf16 v[38:41], v[150:153], v[200:203], v[38:41]
	v_mfma_f32_16x16x32_bf16 v[34:37], v[180:183], v[200:203], v[34:37]
	v_mfma_f32_16x16x32_bf16 v[22:25], v[150:153], v[208:211], v[22:25]
	v_mfma_f32_16x16x32_bf16 v[18:21], v[180:183], v[208:211], v[18:21]
	v_mfma_f32_16x16x32_bf16 v[6:9], v[150:153], v[216:219], v[6:9]
	v_mfma_f32_16x16x32_bf16 v[2:5], v[180:183], v[216:219], v[2:5]
	s_setprio 0
	s_barrier
	s_add_i32 s54, 0, 0x18000
	v_add_u32_e32 v1, s54, v173
	s_add_i32 s55, 0, 0x1c000
	ds_read_b128 v[78:81], v1
	ds_read_b128 v[86:89], v1 offset:1024
	ds_read_b128 v[90:93], v1 offset:2048
	ds_read_b128 v[94:97], v1 offset:3072
	v_add_u32_e32 v1, s55, v173
	ds_read_b128 v[146:149], v1
	ds_read_b128 v[150:153], v1 offset:1024
	ds_read_b128 v[176:179], v1 offset:2048
	ds_read_b128 v[180:183], v1 offset:3072
	s_add_u32 s28, s28, 0xb0000
	s_addc_u32 s29, s29, 0
	s_mov_b32 m0, s36
	ds_read_b128 v[188:191], v186 offset:32768
	ds_read_b128 v[192:195], v186 offset:33792
	ds_read_b128 v[196:199], v186 offset:34816
	ds_read_b128 v[200:203], v186 offset:35840
	ds_read_b128 v[204:207], v186 offset:36864
	ds_read_b128 v[208:211], v186 offset:37888
	ds_read_b128 v[212:215], v186 offset:38912
	ds_read_b128 v[216:219], v186 offset:39936
	s_cmp_eq_u32 s51, 40
	s_cselect_b64 exec, 0, -1
	s_cmp_lg_u32 s33, 0x100
	s_cselect_b64 exec, -1, exec
	global_load_lds_dwordx4 v154, s[28:29]
	s_mov_b32 m0, s37
	s_nop 0
	global_load_lds_dwordx4 v158, s[28:29]
	s_mov_b64 exec, -1
	s_waitcnt vmcnt(8)
	s_waitcnt lgkmcnt(0)
	s_barrier
	s_setprio 1
	v_mfma_f32_16x16x32_bf16 v[142:145], v[78:81], v[188:191], v[142:145]
	v_mfma_f32_16x16x32_bf16 v[138:141], v[90:93], v[188:191], v[138:141]
	v_mfma_f32_16x16x32_bf16 v[126:129], v[78:81], v[196:199], v[126:129]
	v_mfma_f32_16x16x32_bf16 v[122:125], v[90:93], v[196:199], v[122:125]
	v_mfma_f32_16x16x32_bf16 v[110:113], v[78:81], v[204:207], v[110:113]
	v_mfma_f32_16x16x32_bf16 v[106:109], v[90:93], v[204:207], v[106:109]
	v_mfma_f32_16x16x32_bf16 v[82:85], v[78:81], v[212:215], v[82:85]
	v_mfma_f32_16x16x32_bf16 v[74:77], v[90:93], v[212:215], v[74:77]
	v_mfma_f32_16x16x32_bf16 v[142:145], v[86:89], v[192:195], v[142:145]
	v_mfma_f32_16x16x32_bf16 v[138:141], v[94:97], v[192:195], v[138:141]
	v_mfma_f32_16x16x32_bf16 v[126:129], v[86:89], v[200:203], v[126:129]
	v_mfma_f32_16x16x32_bf16 v[122:125], v[94:97], v[200:203], v[122:125]
	v_mfma_f32_16x16x32_bf16 v[110:113], v[86:89], v[208:211], v[110:113]
	v_mfma_f32_16x16x32_bf16 v[106:109], v[94:97], v[208:211], v[106:109]
	v_mfma_f32_16x16x32_bf16 v[82:85], v[86:89], v[216:219], v[82:85]
	v_mfma_f32_16x16x32_bf16 v[74:77], v[94:97], v[216:219], v[74:77]
	v_mfma_f32_16x16x32_bf16 v[134:137], v[146:149], v[188:191], v[134:137]
	v_mfma_f32_16x16x32_bf16 v[130:133], v[176:179], v[188:191], v[130:133]
	v_mfma_f32_16x16x32_bf16 v[118:121], v[146:149], v[196:199], v[118:121]
	v_mfma_f32_16x16x32_bf16 v[114:117], v[176:179], v[196:199], v[114:117]
	v_mfma_f32_16x16x32_bf16 v[102:105], v[146:149], v[204:207], v[102:105]
	v_mfma_f32_16x16x32_bf16 v[98:101], v[176:179], v[204:207], v[98:101]
	v_mfma_f32_16x16x32_bf16 v[70:73], v[146:149], v[212:215], v[70:73]
	v_mfma_f32_16x16x32_bf16 v[66:69], v[176:179], v[212:215], v[66:69]
	v_mfma_f32_16x16x32_bf16 v[134:137], v[150:153], v[192:195], v[134:137]
	v_mfma_f32_16x16x32_bf16 v[130:133], v[180:183], v[192:195], v[130:133]
	v_mfma_f32_16x16x32_bf16 v[118:121], v[150:153], v[200:203], v[118:121]
	v_mfma_f32_16x16x32_bf16 v[114:117], v[180:183], v[200:203], v[114:117]
	v_mfma_f32_16x16x32_bf16 v[102:105], v[150:153], v[208:211], v[102:105]
	v_mfma_f32_16x16x32_bf16 v[98:101], v[180:183], v[208:211], v[98:101]
	v_mfma_f32_16x16x32_bf16 v[70:73], v[150:153], v[216:219], v[70:73]
	v_mfma_f32_16x16x32_bf16 v[66:69], v[180:183], v[216:219], v[66:69]
	s_setprio 0
	s_barrier
	s_add_i32 s28, s54, s31
	s_mov_b32 m0, s28
	ds_read_b128 v[188:191], v186 offset:49152
	ds_read_b128 v[192:195], v186 offset:50176
	ds_read_b128 v[196:199], v186 offset:51200
	ds_read_b128 v[200:203], v186 offset:52224
	ds_read_b128 v[204:207], v186 offset:53248
	ds_read_b128 v[208:211], v186 offset:54272
	ds_read_b128 v[212:215], v186 offset:55296
	ds_read_b128 v[216:219], v186 offset:56320
	s_cmp_eq_u32 s51, 40
	s_cselect_b64 exec, 0, -1
	s_cmp_lg_u32 s33, 0x100
	s_cselect_b64 exec, -1, exec
	global_load_lds_dwordx4 v156, s[98:99]
	s_add_i32 m0, s28, 0x2000
	s_add_u32 s26, s26, 0xb0080
	s_addc_u32 s27, s27, 0
	s_add_i32 s28, s55, s31
	global_load_lds_dwordx4 v160, s[98:99]
	s_mov_b32 m0, s28
	s_nop 0
	global_load_lds_dwordx4 v156, s[26:27]
	s_add_i32 m0, s28, 0x2000
	s_nop 0
	global_load_lds_dwordx4 v160, s[26:27]
	s_mov_b32 m0, s41
	s_nop 0
	global_load_lds_dwordx4 v154, s[100:101]
	s_mov_b32 m0, s42
	s_nop 0
	global_load_lds_dwordx4 v158, s[100:101]
	s_mov_b64 exec, -1
	s_waitcnt vmcnt(8)
	s_waitcnt lgkmcnt(0)
	s_barrier
	s_setprio 1
	v_mfma_f32_16x16x32_bf16 v[62:65], v[78:81], v[188:191], v[62:65]
	v_mfma_f32_16x16x32_bf16 v[58:61], v[90:93], v[188:191], v[58:61]
	v_mfma_f32_16x16x32_bf16 v[46:49], v[78:81], v[196:199], v[46:49]
	v_mfma_f32_16x16x32_bf16 v[42:45], v[90:93], v[196:199], v[42:45]
	v_mfma_f32_16x16x32_bf16 v[30:33], v[78:81], v[204:207], v[30:33]
	v_mfma_f32_16x16x32_bf16 v[26:29], v[90:93], v[204:207], v[26:29]
	v_mfma_f32_16x16x32_bf16 v[14:17], v[78:81], v[212:215], v[14:17]
	v_mfma_f32_16x16x32_bf16 v[10:13], v[90:93], v[212:215], v[10:13]
	v_mfma_f32_16x16x32_bf16 v[62:65], v[86:89], v[192:195], v[62:65]
	v_mfma_f32_16x16x32_bf16 v[58:61], v[94:97], v[192:195], v[58:61]
	v_mfma_f32_16x16x32_bf16 v[46:49], v[86:89], v[200:203], v[46:49]
	v_mfma_f32_16x16x32_bf16 v[42:45], v[94:97], v[200:203], v[42:45]
	v_mfma_f32_16x16x32_bf16 v[30:33], v[86:89], v[208:211], v[30:33]
	v_mfma_f32_16x16x32_bf16 v[26:29], v[94:97], v[208:211], v[26:29]
	v_mfma_f32_16x16x32_bf16 v[14:17], v[86:89], v[216:219], v[14:17]
	v_mfma_f32_16x16x32_bf16 v[10:13], v[94:97], v[216:219], v[10:13]
	v_mfma_f32_16x16x32_bf16 v[54:57], v[146:149], v[188:191], v[54:57]
	v_mfma_f32_16x16x32_bf16 v[50:53], v[176:179], v[188:191], v[50:53]
	v_mfma_f32_16x16x32_bf16 v[38:41], v[146:149], v[196:199], v[38:41]
	v_mfma_f32_16x16x32_bf16 v[34:37], v[176:179], v[196:199], v[34:37]
	v_mfma_f32_16x16x32_bf16 v[22:25], v[146:149], v[204:207], v[22:25]
	v_mfma_f32_16x16x32_bf16 v[18:21], v[176:179], v[204:207], v[18:21]
	v_mfma_f32_16x16x32_bf16 v[6:9], v[146:149], v[212:215], v[6:9]
	v_mfma_f32_16x16x32_bf16 v[2:5], v[176:179], v[212:215], v[2:5]
	v_mfma_f32_16x16x32_bf16 v[54:57], v[150:153], v[192:195], v[54:57]
	v_mfma_f32_16x16x32_bf16 v[50:53], v[180:183], v[192:195], v[50:53]
	v_mfma_f32_16x16x32_bf16 v[38:41], v[150:153], v[200:203], v[38:41]
	v_mfma_f32_16x16x32_bf16 v[34:37], v[180:183], v[200:203], v[34:37]
	v_mfma_f32_16x16x32_bf16 v[22:25], v[150:153], v[208:211], v[22:25]
	v_mfma_f32_16x16x32_bf16 v[18:21], v[180:183], v[208:211], v[18:21]
	v_mfma_f32_16x16x32_bf16 v[6:9], v[150:153], v[216:219], v[6:9]
	v_mfma_f32_16x16x32_bf16 v[2:5], v[180:183], v[216:219], v[2:5]
	s_setprio 0
	s_barrier
	s_add_i32 s51, s51, 2
	s_add_u32 s24, s24, 0x100
	s_addc_u32 s25, s25, 0
	s_add_u32 s49, s49, 0x100
	s_addc_u32 s50, s50, 0
	s_cmp_gt_u32 s51, 41

.LBB0_1462:
	s_add_u32 s16, s16, 0xb0080
	s_addc_u32 s17, s17, 0
	s_add_u32 s43, s18, 0x100
	s_addc_u32 s44, s19, 0
	s_mov_b32 s45, -2
	ds_read_b128 v[128:131], v169
	ds_read_b128 v[132:135], v169 offset:1024
	ds_read_b128 v[136:139], v169 offset:2048
	ds_read_b128 v[140:143], v169 offset:3072
	ds_read_b128 v[160:163], v170
	ds_read_b128 v[172:175], v170 offset:1024
	ds_read_b128 v[176:179], v170 offset:2048
	ds_read_b128 v[180:183], v170 offset:3072
	s_add_u32 s18, s16, 0xfff50080
	s_addc_u32 s19, s17, -1
	s_cmp_eq_u32 s45, 40
	s_cselect_b32 s21, s5, s19
	s_cselect_b32 s20, s4, s18
	s_cselect_b32 s19, s15, s44
	s_cselect_b32 s18, s14, s43
	s_add_i32 m0, s26, 0xc000
	ds_read_b128 v[184:187], v171
	ds_read_b128 v[188:191], v171 offset:1024
	ds_read_b128 v[192:195], v171 offset:2048
	ds_read_b128 v[196:199], v171 offset:3072
	ds_read_b128 v[200:203], v171 offset:4096
	ds_read_b128 v[204:207], v171 offset:5120
	ds_read_b128 v[208:211], v171 offset:6144
	ds_read_b128 v[212:215], v171 offset:7168
	global_load_lds_dwordx4 v152, s[16:17]
	s_add_i32 m0, s26, 0xe000
	s_nop 0
	global_load_lds_dwordx4 v154, s[16:17]
	s_waitcnt vmcnt(8)
	s_waitcnt lgkmcnt(0)
	s_barrier
	s_setprio 1
	v_mfma_f32_16x16x32_bf16 v[124:127], v[128:131], v[184:187], 0
	v_mfma_f32_16x16x32_bf16 v[120:123], v[136:139], v[184:187], 0
	v_mfma_f32_16x16x32_bf16 v[116:119], v[128:131], v[192:195], 0
	v_mfma_f32_16x16x32_bf16 v[108:111], v[136:139], v[192:195], 0
	v_mfma_f32_16x16x32_bf16 v[92:95], v[128:131], v[200:203], 0
	v_mfma_f32_16x16x32_bf16 v[88:91], v[136:139], v[200:203], 0
	v_mfma_f32_16x16x32_bf16 v[84:87], v[128:131], v[208:211], 0
	v_mfma_f32_16x16x32_bf16 v[80:83], v[136:139], v[208:211], 0
	v_mfma_f32_16x16x32_bf16 v[124:127], v[132:135], v[188:191], v[124:127]
	v_mfma_f32_16x16x32_bf16 v[120:123], v[140:143], v[188:191], v[120:123]
	v_mfma_f32_16x16x32_bf16 v[116:119], v[132:135], v[196:199], v[116:119]
	v_mfma_f32_16x16x32_bf16 v[108:111], v[140:143], v[196:199], v[108:111]
	v_mfma_f32_16x16x32_bf16 v[92:95], v[132:135], v[204:207], v[92:95]
	v_mfma_f32_16x16x32_bf16 v[88:91], v[140:143], v[204:207], v[88:91]
	v_mfma_f32_16x16x32_bf16 v[84:87], v[132:135], v[212:215], v[84:87]
	v_mfma_f32_16x16x32_bf16 v[80:83], v[140:143], v[212:215], v[80:83]
	v_mfma_f32_16x16x32_bf16 v[112:115], v[160:163], v[184:187], 0
	v_mfma_f32_16x16x32_bf16 v[104:107], v[176:179], v[184:187], 0
	v_mfma_f32_16x16x32_bf16 v[100:103], v[160:163], v[192:195], 0
	v_mfma_f32_16x16x32_bf16 v[96:99], v[176:179], v[192:195], 0
	v_mfma_f32_16x16x32_bf16 v[76:79], v[160:163], v[200:203], 0
	v_mfma_f32_16x16x32_bf16 v[72:75], v[176:179], v[200:203], 0
	v_mfma_f32_16x16x32_bf16 v[68:71], v[160:163], v[208:211], 0
	v_mfma_f32_16x16x32_bf16 v[64:67], v[176:179], v[208:211], 0
	v_mfma_f32_16x16x32_bf16 v[112:115], v[172:175], v[188:191], v[112:115]
	v_mfma_f32_16x16x32_bf16 v[104:107], v[180:183], v[188:191], v[104:107]
	v_mfma_f32_16x16x32_bf16 v[100:103], v[172:175], v[196:199], v[100:103]
	v_mfma_f32_16x16x32_bf16 v[96:99], v[180:183], v[196:199], v[96:99]
	v_mfma_f32_16x16x32_bf16 v[76:79], v[172:175], v[204:207], v[76:79]
	v_mfma_f32_16x16x32_bf16 v[72:75], v[180:183], v[204:207], v[72:75]
	v_mfma_f32_16x16x32_bf16 v[68:71], v[172:175], v[212:215], v[68:71]
	v_mfma_f32_16x16x32_bf16 v[64:67], v[180:183], v[212:215], v[64:67]
	s_setprio 0
	s_barrier
	s_add_u32 s98, s18, 0x80
	s_addc_u32 s99, s19, 0
	s_add_u32 s100, s20, 0x80
	s_addc_u32 s101, s21, 0
	s_add_i32 s46, s37, s25
	s_mov_b32 m0, s46
	ds_read_b128 v[184:187], v171 offset:16384
	ds_read_b128 v[188:191], v171 offset:17408
	ds_read_b128 v[192:195], v171 offset:18432
	ds_read_b128 v[196:199], v171 offset:19456
	ds_read_b128 v[200:203], v171 offset:20480
	ds_read_b128 v[204:207], v171 offset:21504
	ds_read_b128 v[208:211], v171 offset:22528
	ds_read_b128 v[212:215], v171 offset:23552
	s_cmp_eq_u32 s45, 40
	s_cselect_b64 exec, 0, -1
	s_cmp_lg_u32 s33, 0x100
	s_cselect_b64 exec, -1, exec
	global_load_lds_dwordx4 v146, s[18:19]
	s_add_i32 m0, s46, 0x2000
	s_add_u32 s46, s18, 0xb0000
	s_addc_u32 s47, s19, 0
	s_add_i32 s48, s38, s25
	global_load_lds_dwordx4 v150, s[18:19]
	s_mov_b32 m0, s48
	s_nop 0
	global_load_lds_dwordx4 v146, s[46:47]
	s_add_i32 m0, s48, 0x2000
	s_nop 0
	global_load_lds_dwordx4 v150, s[46:47]
	s_mov_b32 m0, s26
	s_nop 0
	global_load_lds_dwordx4 v144, s[20:21]
	s_mov_b32 m0, s27
	s_nop 0
	global_load_lds_dwordx4 v148, s[20:21]
	s_mov_b64 exec, -1
	s_waitcnt vmcnt(8)
	s_waitcnt lgkmcnt(0)
	s_barrier
	s_setprio 1
	v_mfma_f32_16x16x32_bf16 v[60:63], v[128:131], v[184:187], 0
	v_mfma_f32_16x16x32_bf16 v[56:59], v[136:139], v[184:187], 0
	v_mfma_f32_16x16x32_bf16 v[52:55], v[128:131], v[192:195], 0
	v_mfma_f32_16x16x32_bf16 v[48:51], v[136:139], v[192:195], 0
	v_mfma_f32_16x16x32_bf16 v[28:31], v[128:131], v[200:203], 0
	v_mfma_f32_16x16x32_bf16 v[24:27], v[136:139], v[200:203], 0
	v_mfma_f32_16x16x32_bf16 v[20:23], v[128:131], v[208:211], 0
	v_mfma_f32_16x16x32_bf16 v[16:19], v[136:139], v[208:211], 0
	v_mfma_f32_16x16x32_bf16 v[60:63], v[132:135], v[188:191], v[60:63]
	v_mfma_f32_16x16x32_bf16 v[56:59], v[140:143], v[188:191], v[56:59]
	v_mfma_f32_16x16x32_bf16 v[52:55], v[132:135], v[196:199], v[52:55]
	v_mfma_f32_16x16x32_bf16 v[48:51], v[140:143], v[196:199], v[48:51]
	v_mfma_f32_16x16x32_bf16 v[28:31], v[132:135], v[204:207], v[28:31]
	v_mfma_f32_16x16x32_bf16 v[24:27], v[140:143], v[204:207], v[24:27]
	v_mfma_f32_16x16x32_bf16 v[20:23], v[132:135], v[212:215], v[20:23]
	v_mfma_f32_16x16x32_bf16 v[16:19], v[140:143], v[212:215], v[16:19]
	v_mfma_f32_16x16x32_bf16 v[44:47], v[160:163], v[184:187], 0
	v_mfma_f32_16x16x32_bf16 v[40:43], v[176:179], v[184:187], 0
	v_mfma_f32_16x16x32_bf16 v[36:39], v[160:163], v[192:195], 0
	v_mfma_f32_16x16x32_bf16 v[32:35], v[176:179], v[192:195], 0
	v_mfma_f32_16x16x32_bf16 v[12:15], v[160:163], v[200:203], 0
	v_mfma_f32_16x16x32_bf16 v[8:11], v[176:179], v[200:203], 0
	v_mfma_f32_16x16x32_bf16 v[4:7], v[160:163], v[208:211], 0
	v_mfma_f32_16x16x32_bf16 v[0:3], v[176:179], v[208:211], 0
	v_mfma_f32_16x16x32_bf16 v[44:47], v[172:175], v[188:191], v[44:47]
	v_mfma_f32_16x16x32_bf16 v[40:43], v[180:183], v[188:191], v[40:43]
	v_mfma_f32_16x16x32_bf16 v[36:39], v[172:175], v[196:199], v[36:39]
	v_mfma_f32_16x16x32_bf16 v[32:35], v[180:183], v[196:199], v[32:35]
	v_mfma_f32_16x16x32_bf16 v[12:15], v[172:175], v[204:207], v[12:15]
	v_mfma_f32_16x16x32_bf16 v[8:11], v[180:183], v[204:207], v[8:11]
	v_mfma_f32_16x16x32_bf16 v[4:7], v[172:175], v[212:215], v[4:7]
	v_mfma_f32_16x16x32_bf16 v[0:3], v[180:183], v[212:215], v[0:3]
	s_setprio 0
	s_barrier
	s_add_i32 s46, 0, 0x18000
	s_add_i32 s47, 0, 0x1c000
	v_add_u32_e32 v140, s46, v167
	v_add_u32_e32 v180, s47, v167
	ds_read_b128 v[128:131], v140
	ds_read_b128 v[132:135], v140 offset:1024
	ds_read_b128 v[136:139], v140 offset:2048
	ds_read_b128 v[140:143], v140 offset:3072
	ds_read_b128 v[160:163], v180
	ds_read_b128 v[172:175], v180 offset:1024
	ds_read_b128 v[176:179], v180 offset:2048
	ds_read_b128 v[180:183], v180 offset:3072
	s_add_u32 s20, s20, 0xb0000
	s_addc_u32 s21, s21, 0
	s_mov_b32 m0, s28
	ds_read_b128 v[184:187], v171 offset:32768
	ds_read_b128 v[188:191], v171 offset:33792
	ds_read_b128 v[192:195], v171 offset:34816
	ds_read_b128 v[196:199], v171 offset:35840
	ds_read_b128 v[200:203], v171 offset:36864
	ds_read_b128 v[204:207], v171 offset:37888
	ds_read_b128 v[208:211], v171 offset:38912
	ds_read_b128 v[212:215], v171 offset:39936
	s_cmp_eq_u32 s45, 40
	s_cselect_b64 exec, 0, -1
	s_cmp_lg_u32 s33, 0x100
	s_cselect_b64 exec, -1, exec
	global_load_lds_dwordx4 v144, s[20:21]
	s_mov_b32 m0, s29
	s_nop 0
	global_load_lds_dwordx4 v148, s[20:21]
	s_mov_b64 exec, -1
	s_waitcnt vmcnt(8)
	s_waitcnt lgkmcnt(0)
	s_barrier
	s_setprio 1
	v_mfma_f32_16x16x32_bf16 v[124:127], v[128:131], v[184:187], v[124:127]
	v_mfma_f32_16x16x32_bf16 v[120:123], v[136:139], v[184:187], v[120:123]
	v_mfma_f32_16x16x32_bf16 v[116:119], v[128:131], v[192:195], v[116:119]
	v_mfma_f32_16x16x32_bf16 v[108:111], v[136:139], v[192:195], v[108:111]
	v_mfma_f32_16x16x32_bf16 v[92:95], v[128:131], v[200:203], v[92:95]
	v_mfma_f32_16x16x32_bf16 v[88:91], v[136:139], v[200:203], v[88:91]
	v_mfma_f32_16x16x32_bf16 v[84:87], v[128:131], v[208:211], v[84:87]
	v_mfma_f32_16x16x32_bf16 v[80:83], v[136:139], v[208:211], v[80:83]
	v_mfma_f32_16x16x32_bf16 v[124:127], v[132:135], v[188:191], v[124:127]
	v_mfma_f32_16x16x32_bf16 v[120:123], v[140:143], v[188:191], v[120:123]
	v_mfma_f32_16x16x32_bf16 v[116:119], v[132:135], v[196:199], v[116:119]
	v_mfma_f32_16x16x32_bf16 v[108:111], v[140:143], v[196:199], v[108:111]
	v_mfma_f32_16x16x32_bf16 v[92:95], v[132:135], v[204:207], v[92:95]
	v_mfma_f32_16x16x32_bf16 v[88:91], v[140:143], v[204:207], v[88:91]
	v_mfma_f32_16x16x32_bf16 v[84:87], v[132:135], v[212:215], v[84:87]
	v_mfma_f32_16x16x32_bf16 v[80:83], v[140:143], v[212:215], v[80:83]
	v_mfma_f32_16x16x32_bf16 v[112:115], v[160:163], v[184:187], v[112:115]
	v_mfma_f32_16x16x32_bf16 v[104:107], v[176:179], v[184:187], v[104:107]
	v_mfma_f32_16x16x32_bf16 v[100:103], v[160:163], v[192:195], v[100:103]
	v_mfma_f32_16x16x32_bf16 v[96:99], v[176:179], v[192:195], v[96:99]
	v_mfma_f32_16x16x32_bf16 v[76:79], v[160:163], v[200:203], v[76:79]
	v_mfma_f32_16x16x32_bf16 v[72:75], v[176:179], v[200:203], v[72:75]
	v_mfma_f32_16x16x32_bf16 v[68:71], v[160:163], v[208:211], v[68:71]
	v_mfma_f32_16x16x32_bf16 v[64:67], v[176:179], v[208:211], v[64:67]
	v_mfma_f32_16x16x32_bf16 v[112:115], v[172:175], v[188:191], v[112:115]
	v_mfma_f32_16x16x32_bf16 v[104:107], v[180:183], v[188:191], v[104:107]
	v_mfma_f32_16x16x32_bf16 v[100:103], v[172:175], v[196:199], v[100:103]
	v_mfma_f32_16x16x32_bf16 v[96:99], v[180:183], v[196:199], v[96:99]
	v_mfma_f32_16x16x32_bf16 v[76:79], v[172:175], v[204:207], v[76:79]
	v_mfma_f32_16x16x32_bf16 v[72:75], v[180:183], v[204:207], v[72:75]
	v_mfma_f32_16x16x32_bf16 v[68:71], v[172:175], v[212:215], v[68:71]
	v_mfma_f32_16x16x32_bf16 v[64:67], v[180:183], v[212:215], v[64:67]
	s_setprio 0
	s_barrier
	s_add_i32 s20, s46, s25
	s_mov_b32 m0, s20
	ds_read_b128 v[184:187], v171 offset:49152
	ds_read_b128 v[188:191], v171 offset:50176
	ds_read_b128 v[192:195], v171 offset:51200
	ds_read_b128 v[196:199], v171 offset:52224
	ds_read_b128 v[200:203], v171 offset:53248
	ds_read_b128 v[204:207], v171 offset:54272
	ds_read_b128 v[208:211], v171 offset:55296
	ds_read_b128 v[212:215], v171 offset:56320
	s_cmp_eq_u32 s45, 40
	s_cselect_b64 exec, 0, -1
	s_cmp_lg_u32 s33, 0x100
	s_cselect_b64 exec, -1, exec
	global_load_lds_dwordx4 v146, s[98:99]
	s_add_i32 m0, s20, 0x2000
	s_add_u32 s18, s18, 0xb0080
	s_addc_u32 s19, s19, 0
	s_add_i32 s20, s47, s25
	global_load_lds_dwordx4 v150, s[98:99]
	s_mov_b32 m0, s20
	s_nop 0
	global_load_lds_dwordx4 v146, s[18:19]
	s_add_i32 m0, s20, 0x2000
	s_nop 0
	global_load_lds_dwordx4 v150, s[18:19]
	s_mov_b32 m0, s35
	s_nop 0
	global_load_lds_dwordx4 v144, s[100:101]
	s_mov_b32 m0, s36
	s_nop 0
	global_load_lds_dwordx4 v148, s[100:101]
	s_mov_b64 exec, -1
	s_waitcnt vmcnt(8)
	s_waitcnt lgkmcnt(0)
	s_barrier
	s_setprio 1
	v_mfma_f32_16x16x32_bf16 v[60:63], v[128:131], v[184:187], v[60:63]
	v_mfma_f32_16x16x32_bf16 v[56:59], v[136:139], v[184:187], v[56:59]
	v_mfma_f32_16x16x32_bf16 v[52:55], v[128:131], v[192:195], v[52:55]
	v_mfma_f32_16x16x32_bf16 v[48:51], v[136:139], v[192:195], v[48:51]
	v_mfma_f32_16x16x32_bf16 v[28:31], v[128:131], v[200:203], v[28:31]
	v_mfma_f32_16x16x32_bf16 v[24:27], v[136:139], v[200:203], v[24:27]
	v_mfma_f32_16x16x32_bf16 v[20:23], v[128:131], v[208:211], v[20:23]
	v_mfma_f32_16x16x32_bf16 v[16:19], v[136:139], v[208:211], v[16:19]
	v_mfma_f32_16x16x32_bf16 v[60:63], v[132:135], v[188:191], v[60:63]
	v_mfma_f32_16x16x32_bf16 v[56:59], v[140:143], v[188:191], v[56:59]
	v_mfma_f32_16x16x32_bf16 v[52:55], v[132:135], v[196:199], v[52:55]
	v_mfma_f32_16x16x32_bf16 v[48:51], v[140:143], v[196:199], v[48:51]
	v_mfma_f32_16x16x32_bf16 v[28:31], v[132:135], v[204:207], v[28:31]
	v_mfma_f32_16x16x32_bf16 v[24:27], v[140:143], v[204:207], v[24:27]
	v_mfma_f32_16x16x32_bf16 v[20:23], v[132:135], v[212:215], v[20:23]
	v_mfma_f32_16x16x32_bf16 v[16:19], v[140:143], v[212:215], v[16:19]
	v_mfma_f32_16x16x32_bf16 v[44:47], v[160:163], v[184:187], v[44:47]
	v_mfma_f32_16x16x32_bf16 v[40:43], v[176:179], v[184:187], v[40:43]
	v_mfma_f32_16x16x32_bf16 v[36:39], v[160:163], v[192:195], v[36:39]
	v_mfma_f32_16x16x32_bf16 v[32:35], v[176:179], v[192:195], v[32:35]
	v_mfma_f32_16x16x32_bf16 v[12:15], v[160:163], v[200:203], v[12:15]
	v_mfma_f32_16x16x32_bf16 v[8:11], v[176:179], v[200:203], v[8:11]
	v_mfma_f32_16x16x32_bf16 v[4:7], v[160:163], v[208:211], v[4:7]
	v_mfma_f32_16x16x32_bf16 v[0:3], v[176:179], v[208:211], v[0:3]
	v_mfma_f32_16x16x32_bf16 v[44:47], v[172:175], v[188:191], v[44:47]
	v_mfma_f32_16x16x32_bf16 v[40:43], v[180:183], v[188:191], v[40:43]
	v_mfma_f32_16x16x32_bf16 v[36:39], v[172:175], v[196:199], v[36:39]
	v_mfma_f32_16x16x32_bf16 v[32:35], v[180:183], v[196:199], v[32:35]
	v_mfma_f32_16x16x32_bf16 v[12:15], v[172:175], v[204:207], v[12:15]
	v_mfma_f32_16x16x32_bf16 v[8:11], v[180:183], v[204:207], v[8:11]
	v_mfma_f32_16x16x32_bf16 v[4:7], v[172:175], v[212:215], v[4:7]
	v_mfma_f32_16x16x32_bf16 v[0:3], v[180:183], v[212:215], v[0:3]
	s_setprio 0
	s_barrier
	s_add_i32 s45, s45, 2
	s_add_u32 s16, s16, 0x100
	s_addc_u32 s17, s17, 0
	s_add_u32 s43, s43, 0x100
	s_addc_u32 s44, s44, 0
	s_cmp_gt_u32 s45, 41
